# speedup vs baseline: 1.0129x; 1.0041x over previous
; #define MFMA(a, b, c) __builtin_amdgcn_mfma_f32_16x16x32_bf16(a, b, c, 0, 0, 0)
; template <class Epi>
; __device__ __forceinline__ void gemm_phase(const u16* __restrict__ A, int lda, const u16* __restrict__ Bt, int ldb, int K,
;                                            int MT, int NT, bool lat_only, char* smem, Epi epi) {
;     ...
;     for (int kt = 0; kt < nk; ++kt) {
;       int stg2 = stg + 2;
;       if (stg2 >= 3) stg2 -= 3;
;       if (!late && kt + 2 < nk) GSTAGE(stg2, kt + 2);
;       const char* sa = smem + stg * 49152;
;       const char* sb = sa + 32768;
; #pragma unroll
;       for (int ks = 0; ks < 2; ++ks) {
;         bf16x8 af[4], bf[4];
; #pragma unroll
;         for (int m = 0; m < 4; ++m) af[m] = *(const bf16x8*)(sa + sw128(wr * 64 + m * 16 + fr, ks * 4 + fq));
; #pragma unroll
;         for (int n = 0; n < 4; ++n) bf[n] = *(const bf16x8*)(sb + sw128(wc * 64 + n * 16 + fr, ks * 4 + fq));
;         __builtin_amdgcn_s_setprio(1);
; #pragma unroll
;         for (int m = 0; m < 4; ++m)
; #pragma unroll
;           for (int n = 0; n < 4; ++n) acc[m][n] = MFMA(bf[n], af[m], acc[m][n]);
;         __builtin_amdgcn_s_setprio(0);
;       }
.LBB0_399:
	s_mul_i32 s14, s2, 0xc000
	s_addk_i32 s14, 0x190
	v_add_u32_e32 v133, s14, v129
	v_add_u32_e32 v146, v133, v128
	v_add3_u32 v162, s14, v128, v130
	ds_read_b128 v[134:137], v146
	ds_read_b128 v[138:141], v146 offset:2048
	ds_read_b128 v[142:145], v146 offset:4096
	ds_read_b128 v[146:149], v146 offset:6144
	ds_read_b128 v[150:153], v162 offset:32768
	ds_read_b128 v[154:157], v162 offset:34816
	ds_read_b128 v[158:161], v162 offset:36864
	ds_read_b128 v[162:165], v162 offset:38912
	s_cmp_gt_i32 s2, 0
	s_cselect_b32 s12, -1, 2
	s_add_i32 s26, s12, s2
	s_cmp_gt_u32 s5, 13
	s_cselect_b64 s[12:13], -1, 0
	s_cmp_lt_u32 s5, 14
	s_cselect_b64 s[14:15], -1, 0
	s_mul_i32 s26, s26, 0xc000
	s_and_b64 s[86:87], s[0:1], s[14:15]
	v_lshl_add_u64 v[124:125], v[94:95], 0, s[10:11]
	v_lshl_add_u64 v[122:123], v[92:93], 0, s[10:11]
	v_lshl_add_u64 v[102:103], v[90:91], 0, s[10:11]
	v_lshl_add_u64 v[100:101], v[88:89], 0, s[10:11]
	v_lshl_add_u64 v[98:99], v[86:87], 0, s[10:11]
	v_lshl_add_u64 v[96:97], v[84:85], 0, s[10:11]
	v_add_u32_e32 v132, s26, v121
	s_and_saveexec_b64 s[14:15], s[86:87]
	s_cbranch_execz .LBB0_401
	v_readfirstlane_b32 s26, v132
	v_add_u32_e32 v133, 0x2000, v132
	s_mov_b32 m0, s26
	v_readfirstlane_b32 s26, v133
	v_add_u32_e32 v133, 0x4000, v132
	global_load_lds_dwordx4 v[124:125], off
	s_mov_b32 m0, s26
	v_readfirstlane_b32 s26, v133
	v_add_u32_e32 v133, 0x6000, v132
	global_load_lds_dwordx4 v[122:123], off
	s_mov_b32 m0, s26
	v_readfirstlane_b32 s26, v133
	v_add_u32_e32 v133, 0x8000, v132
	global_load_lds_dwordx4 v[102:103], off
	s_mov_b32 m0, s26
	v_readfirstlane_b32 s26, v133
	v_add_u32_e32 v133, 0xa000, v132
	global_load_lds_dwordx4 v[100:101], off
	s_mov_b32 m0, s26
	v_readfirstlane_b32 s26, v133
	global_load_lds_dwordx4 v[98:99], off
	s_mov_b32 m0, s26
	s_nop 0
	global_load_lds_dwordx4 v[96:97], off
.LBB0_401:
	s_or_b64 exec, exec, s[14:15]
	s_mul_i32 s14, s2, 0xc000
	s_addk_i32 s14, 0x190
	v_add_u32_e32 v133, s14, v129
	v_add_u32_e32 v226, s14, v131
	v_add_u32_e32 v227, v226, v129
	v_add_u32_e32 v228, v133, v131
	ds_read_b128 v[170:173], v227
	ds_read_b128 v[174:177], v228 offset:2048
	ds_read_b128 v[178:181], v228 offset:4096
	ds_read_b128 v[182:185], v228 offset:6144
	v_add_u32_e32 v228, v226, v130
	ds_read_b128 v[186:189], v228 offset:32768
	ds_read_b128 v[190:193], v228 offset:34816
	ds_read_b128 v[194:197], v228 offset:36864
	ds_read_b128 v[198:201], v228 offset:38912
	s_cmp_lg_u32 s0, 0
	s_cbranch_scc1 .Lsr399_1
	s_setprio 1
.Lsr399_1:
	s_waitcnt lgkmcnt(8)
	v_mfma_f32_16x16x32_bf16 v[60:63], v[150:153], v[134:137], v[60:63]
	v_mfma_f32_16x16x32_bf16 v[56:59], v[154:157], v[134:137], v[56:59]
	v_mfma_f32_16x16x32_bf16 v[52:55], v[158:161], v[134:137], v[52:55]
	v_mfma_f32_16x16x32_bf16 v[48:51], v[162:165], v[134:137], v[48:51]
	v_mfma_f32_16x16x32_bf16 v[44:47], v[150:153], v[138:141], v[44:47]
	v_mfma_f32_16x16x32_bf16 v[40:43], v[154:157], v[138:141], v[40:43]
	v_mfma_f32_16x16x32_bf16 v[36:39], v[158:161], v[138:141], v[36:39]
	v_mfma_f32_16x16x32_bf16 v[32:35], v[162:165], v[138:141], v[32:35]
	v_mfma_f32_16x16x32_bf16 v[28:31], v[150:153], v[142:145], v[28:31]
	v_mfma_f32_16x16x32_bf16 v[24:27], v[154:157], v[142:145], v[24:27]
	v_mfma_f32_16x16x32_bf16 v[20:23], v[158:161], v[142:145], v[20:23]
	v_mfma_f32_16x16x32_bf16 v[16:19], v[162:165], v[142:145], v[16:19]
	v_mfma_f32_16x16x32_bf16 v[12:15], v[150:153], v[146:149], v[12:15]
	v_mfma_f32_16x16x32_bf16 v[8:11], v[154:157], v[146:149], v[8:11]
	v_mfma_f32_16x16x32_bf16 v[4:7], v[158:161], v[146:149], v[4:7]
	v_mfma_f32_16x16x32_bf16 v[0:3], v[162:165], v[146:149], v[0:3]
	s_waitcnt lgkmcnt(0)
	v_mfma_f32_16x16x32_bf16 v[60:63], v[186:189], v[170:173], v[60:63]
	v_mfma_f32_16x16x32_bf16 v[56:59], v[190:193], v[170:173], v[56:59]
	v_mfma_f32_16x16x32_bf16 v[52:55], v[194:197], v[170:173], v[52:55]
	v_mfma_f32_16x16x32_bf16 v[48:51], v[198:201], v[170:173], v[48:51]
	v_mfma_f32_16x16x32_bf16 v[44:47], v[186:189], v[174:177], v[44:47]
	v_mfma_f32_16x16x32_bf16 v[40:43], v[190:193], v[174:177], v[40:43]
	v_mfma_f32_16x16x32_bf16 v[36:39], v[194:197], v[174:177], v[36:39]
	v_mfma_f32_16x16x32_bf16 v[32:35], v[198:201], v[174:177], v[32:35]
	v_mfma_f32_16x16x32_bf16 v[28:31], v[186:189], v[178:181], v[28:31]
	v_mfma_f32_16x16x32_bf16 v[24:27], v[190:193], v[178:181], v[24:27]
	v_mfma_f32_16x16x32_bf16 v[20:23], v[194:197], v[178:181], v[20:23]
	v_mfma_f32_16x16x32_bf16 v[16:19], v[198:201], v[178:181], v[16:19]
	v_mfma_f32_16x16x32_bf16 v[12:15], v[186:189], v[182:185], v[12:15]
	v_mfma_f32_16x16x32_bf16 v[8:11], v[190:193], v[182:185], v[8:11]
	v_mfma_f32_16x16x32_bf16 v[4:7], v[194:197], v[182:185], v[4:7]
	v_mfma_f32_16x16x32_bf16 v[0:3], v[198:201], v[182:185], v[0:3]
	s_cmp_lg_u32 s0, 0
	s_cbranch_scc0 .Lsr399_0
	s_setprio 0

; template <class Epi>
; __device__ __forceinline__ void gemm_phase(const u16* __restrict__ A, int lda, const u16* __restrict__ Bt, int ldb, int K,
;                                            int MT, int NT, bool lat_only, char* smem, Epi epi) {
;     ...
;     for (int kt = 0; kt < nk; ++kt) {
;       int stg2 = stg + 2;
;       if (stg2 >= 3) stg2 -= 3;
;       if (!late && kt + 2 < nk) GSTAGE(stg2, kt + 2);
;       const char* sa = smem + stg * 49152;
;       const char* sb = sa + 32768;
; #pragma unroll
;       for (int ks = 0; ks < 2; ++ks) {
;         bf16x8 af[4], bf[4];
; #pragma unroll
;         for (int m = 0; m < 4; ++m) af[m] = *(const bf16x8*)(sa + sw128(wr * 64 + m * 16 + fr, ks * 4 + fq));
; #pragma unroll
;         for (int n = 0; n < 4; ++n) bf[n] = *(const bf16x8*)(sb + sw128(wc * 64 + n * 16 + fr, ks * 4 + fq));
;         __builtin_amdgcn_s_setprio(1);
.LBB0_443:
	s_mul_i32 s14, s7, 0xc000
	s_addk_i32 s14, 0x190
	v_add_u32_e32 v133, s14, v128
	v_add_u32_e32 v146, v133, v129
	v_add_u32_e32 v133, v133, v130
	ds_read_b128 v[134:137], v146
	ds_read_b128 v[138:141], v146 offset:2048
	ds_read_b128 v[142:145], v146 offset:4096
	ds_read_b128 v[146:149], v146 offset:6144
	ds_read_b128 v[150:153], v133 offset:32768
	ds_read_b128 v[154:157], v133 offset:34816
	ds_read_b128 v[158:161], v133 offset:36864
	ds_read_b128 v[162:165], v133 offset:38912
	s_cmp_gt_i32 s7, 0
	s_cselect_b32 s12, -1, 2
	s_add_i32 s40, s12, s7
	s_cmp_gt_u32 s9, 13
	s_cselect_b64 s[12:13], -1, 0
	s_cmp_lt_u32 s9, 14
	s_cselect_b64 s[14:15], -1, 0
	s_mul_i32 s40, s40, 0xc000
	s_and_b64 s[74:75], s[0:1], s[14:15]
	v_lshl_add_u64 v[124:125], v[94:95], 0, s[10:11]
	v_lshl_add_u64 v[122:123], v[92:93], 0, s[10:11]
	v_lshl_add_u64 v[102:103], v[90:91], 0, s[10:11]
	v_lshl_add_u64 v[100:101], v[88:89], 0, s[10:11]
	v_lshl_add_u64 v[98:99], v[86:87], 0, s[10:11]
	v_lshl_add_u64 v[96:97], v[84:85], 0, s[10:11]
	v_add_u32_e32 v132, s40, v121
	s_and_saveexec_b64 s[14:15], s[74:75]
	s_cbranch_execz .LBB0_445
	v_readfirstlane_b32 s40, v132
	v_add_u32_e32 v133, 0x2000, v132
	s_mov_b32 m0, s40
	v_readfirstlane_b32 s40, v133
	v_add_u32_e32 v133, 0x4000, v132
	global_load_lds_dwordx4 v[124:125], off
	s_mov_b32 m0, s40
	v_readfirstlane_b32 s40, v133
	v_add_u32_e32 v133, 0x6000, v132
	global_load_lds_dwordx4 v[122:123], off
	s_mov_b32 m0, s40
	v_readfirstlane_b32 s40, v133
	v_add_u32_e32 v133, 0x8000, v132
	global_load_lds_dwordx4 v[102:103], off
	s_mov_b32 m0, s40
	v_readfirstlane_b32 s40, v133
	v_add_u32_e32 v133, 0xa000, v132
	global_load_lds_dwordx4 v[100:101], off
	s_mov_b32 m0, s40
	v_readfirstlane_b32 s40, v133
	global_load_lds_dwordx4 v[98:99], off
	s_mov_b32 m0, s40
	s_nop 0
	global_load_lds_dwordx4 v[96:97], off
.LBB0_445:
	s_or_b64 exec, exec, s[14:15]
	s_mul_i32 s14, s7, 0xc000
	s_addk_i32 s14, 0x190
	v_add_u32_e32 v226, s14, v131
	v_add_u32_e32 v227, v226, v129
	v_add_u32_e32 v226, v226, v130
	ds_read_b128 v[170:173], v227
	ds_read_b128 v[174:177], v227 offset:2048
	ds_read_b128 v[178:181], v227 offset:4096
	ds_read_b128 v[182:185], v227 offset:6144
	ds_read_b128 v[186:189], v226 offset:32768
	ds_read_b128 v[190:193], v226 offset:34816
	ds_read_b128 v[194:197], v226 offset:36864
	ds_read_b128 v[198:201], v226 offset:38912
	s_cmp_lg_u32 s0, 0
	s_cbranch_scc1 .Lsr443_1
	s_setprio 1

; template <class Epi>
; __device__ __forceinline__ void gemm_phase(const u16* __restrict__ A, int lda, const u16* __restrict__ Bt, int ldb, int K,
;                                            int MT, int NT, bool lat_only, char* smem, Epi epi) {
;     ...
;     for (int kt = 0; kt < nk; ++kt) {
;       int stg2 = stg + 2;
;       if (stg2 >= 3) stg2 -= 3;
;       if (!late && kt + 2 < nk) GSTAGE(stg2, kt + 2);
;       const char* sa = smem + stg * 49152;
;       const char* sb = sa + 32768;
; #pragma unroll
;       for (int ks = 0; ks < 2; ++ks) {
;         bf16x8 af[4], bf[4];
; #pragma unroll
;         for (int m = 0; m < 4; ++m) af[m] = *(const bf16x8*)(sa + sw128(wr * 64 + m * 16 + fr, ks * 4 + fq));
; #pragma unroll
;         for (int n = 0; n < 4; ++n) bf[n] = *(const bf16x8*)(sb + sw128(wc * 64 + n * 16 + fr, ks * 4 + fq));
;         __builtin_amdgcn_s_setprio(1);
.LBB0_470:
	s_mul_i32 s40, s15, 0xc000
	s_addk_i32 s40, 0x190
	v_add_u32_e32 v133, s40, v128
	v_add_u32_e32 v146, v133, v129
	v_add_u32_e32 v133, v133, v130
	ds_read_b128 v[134:137], v146
	ds_read_b128 v[138:141], v146 offset:2048
	ds_read_b128 v[142:145], v146 offset:4096
	ds_read_b128 v[146:149], v146 offset:6144
	ds_read_b128 v[150:153], v133 offset:32768
	ds_read_b128 v[154:157], v133 offset:34816
	ds_read_b128 v[158:161], v133 offset:36864
	ds_read_b128 v[162:165], v133 offset:38912
	s_cmp_gt_i32 s15, 0
	s_cselect_b32 s40, -1, 2
	s_add_i32 s40, s40, s15
	s_cmp_gt_u32 s17, 13
	s_cselect_b64 s[44:45], -1, 0
	s_cmp_lt_u32 s17, 14
	s_cselect_b64 s[46:47], -1, 0
	s_mul_i32 s40, s40, 0xc000
	s_and_b64 s[86:87], s[0:1], s[46:47]
	v_lshl_add_u64 v[124:125], v[94:95], 0, s[42:43]
	v_lshl_add_u64 v[122:123], v[92:93], 0, s[42:43]
	v_lshl_add_u64 v[102:103], v[90:91], 0, s[42:43]
	v_lshl_add_u64 v[100:101], v[88:89], 0, s[42:43]
	v_lshl_add_u64 v[98:99], v[86:87], 0, s[42:43]
	v_lshl_add_u64 v[96:97], v[84:85], 0, s[42:43]
	v_add_u32_e32 v132, s40, v121
	s_and_saveexec_b64 s[46:47], s[86:87]
	s_cbranch_execz .LBB0_472
	v_readfirstlane_b32 s40, v132
	v_add_u32_e32 v133, 0x2000, v132
	s_mov_b32 m0, s40
	v_readfirstlane_b32 s40, v133
	v_add_u32_e32 v133, 0x4000, v132
	global_load_lds_dwordx4 v[124:125], off
	s_mov_b32 m0, s40
	v_readfirstlane_b32 s40, v133
	v_add_u32_e32 v133, 0x6000, v132
	global_load_lds_dwordx4 v[122:123], off
	s_mov_b32 m0, s40
	v_readfirstlane_b32 s40, v133
	v_add_u32_e32 v133, 0x8000, v132
	global_load_lds_dwordx4 v[102:103], off
	s_mov_b32 m0, s40
	v_readfirstlane_b32 s40, v133
	v_add_u32_e32 v133, 0xa000, v132
	global_load_lds_dwordx4 v[100:101], off
	s_mov_b32 m0, s40
	v_readfirstlane_b32 s40, v133
	global_load_lds_dwordx4 v[98:99], off
	s_mov_b32 m0, s40
	s_nop 0
	global_load_lds_dwordx4 v[96:97], off
.LBB0_472:
	s_or_b64 exec, exec, s[46:47]
	s_mul_i32 s40, s15, 0xc000
	s_addk_i32 s40, 0x190
	v_add_u32_e32 v226, s40, v131
	v_add_u32_e32 v227, v226, v129
	v_add_u32_e32 v226, v226, v130
	ds_read_b128 v[170:173], v227
	ds_read_b128 v[174:177], v227 offset:2048
	ds_read_b128 v[178:181], v227 offset:4096
	ds_read_b128 v[182:185], v227 offset:6144
	ds_read_b128 v[186:189], v226 offset:32768
	ds_read_b128 v[190:193], v226 offset:34816
	ds_read_b128 v[194:197], v226 offset:36864
	ds_read_b128 v[198:201], v226 offset:38912
	s_cmp_lg_u32 s0, 0
	s_cbranch_scc1 .Lsr470_1
	s_setprio 1

; template <class Epi>
; __device__ __forceinline__ void gemm_phase(const u16* __restrict__ A, int lda, const u16* __restrict__ Bt, int ldb, int K,
;                                            int MT, int NT, bool lat_only, char* smem, Epi epi) {
;     ...
;     for (int kt = 0; kt < nk; ++kt) {
;       int stg2 = stg + 2;
;       if (stg2 >= 3) stg2 -= 3;
;       if (!late && kt + 2 < nk) GSTAGE(stg2, kt + 2);
;       const char* sa = smem + stg * 49152;
;       const char* sb = sa + 32768;
; #pragma unroll
;       for (int ks = 0; ks < 2; ++ks) {
;         bf16x8 af[4], bf[4];
; #pragma unroll
;         for (int m = 0; m < 4; ++m) af[m] = *(const bf16x8*)(sa + sw128(wr * 64 + m * 16 + fr, ks * 4 + fq));
; #pragma unroll
;         for (int n = 0; n < 4; ++n) bf[n] = *(const bf16x8*)(sb + sw128(wc * 64 + n * 16 + fr, ks * 4 + fq));
;         __builtin_amdgcn_s_setprio(1);
.LBB0_916:
	s_mul_i32 s14, s7, 0xc000
	s_addk_i32 s14, 0x190
	v_add_u32_e32 v133, s14, v128
	v_add_u32_e32 v146, v133, v129
	v_add_u32_e32 v133, v133, v130
	ds_read_b128 v[134:137], v146
	ds_read_b128 v[138:141], v146 offset:2048
	ds_read_b128 v[142:145], v146 offset:4096
	ds_read_b128 v[146:149], v146 offset:6144
	ds_read_b128 v[150:153], v133 offset:32768
	ds_read_b128 v[154:157], v133 offset:34816
	ds_read_b128 v[158:161], v133 offset:36864
	ds_read_b128 v[162:165], v133 offset:38912
	s_cmp_gt_i32 s7, 0
	s_cselect_b32 s12, -1, 2
	s_add_i32 s40, s12, s7
	s_cmp_gt_u32 s47, 13
	s_cselect_b64 s[12:13], -1, 0
	s_cmp_lt_u32 s47, 14
	s_cselect_b64 s[14:15], -1, 0
	s_mul_i32 s40, s40, 0xc000
	s_and_b64 s[50:51], s[0:1], s[14:15]
	v_lshl_add_u64 v[124:125], v[94:95], 0, s[10:11]
	v_lshl_add_u64 v[122:123], v[92:93], 0, s[10:11]
	v_lshl_add_u64 v[102:103], v[90:91], 0, s[10:11]
	v_lshl_add_u64 v[100:101], v[88:89], 0, s[10:11]
	v_lshl_add_u64 v[98:99], v[86:87], 0, s[10:11]
	v_lshl_add_u64 v[96:97], v[84:85], 0, s[10:11]
	v_add_u32_e32 v132, s40, v121
	s_and_saveexec_b64 s[14:15], s[50:51]
	s_cbranch_execz .LBB0_918
	v_readfirstlane_b32 s40, v132
	v_add_u32_e32 v133, 0x2000, v132
	s_mov_b32 m0, s40
	v_readfirstlane_b32 s40, v133
	v_add_u32_e32 v133, 0x4000, v132
	global_load_lds_dwordx4 v[124:125], off
	s_mov_b32 m0, s40
	v_readfirstlane_b32 s40, v133
	v_add_u32_e32 v133, 0x6000, v132
	global_load_lds_dwordx4 v[122:123], off
	s_mov_b32 m0, s40
	v_readfirstlane_b32 s40, v133
	v_add_u32_e32 v133, 0x8000, v132
	global_load_lds_dwordx4 v[102:103], off
	s_mov_b32 m0, s40
	v_readfirstlane_b32 s40, v133
	v_add_u32_e32 v133, 0xa000, v132
	global_load_lds_dwordx4 v[100:101], off
	s_mov_b32 m0, s40
	v_readfirstlane_b32 s40, v133
	global_load_lds_dwordx4 v[98:99], off
	s_mov_b32 m0, s40
	s_nop 0
	global_load_lds_dwordx4 v[96:97], off
